# P1 row loop: modulation vectors resident, next-row x prefetch; P0 weight-copy second-round items moved to workgroups 192-255
# speedup vs baseline: 1.0156x; 1.0006x over previous
; #define LAS __attribute__((address_space(3)))
; __device__ __forceinline__ void prep_tr(Frame& F) {
;     {   LAS float* scr = (LAS float*)(F.lds + F.wave * 16640);
;         const int gw = F.bid * 8 + F.wave, NGW = F.G * 8;
;         constexpr int I1 = (1024 / 64) * (8192 / 64), I2 = (2048 / 64) * (1024 / 64);
;         for (int it = gw; it < I1 + I2; it += NGW) {
;             int rI = it;
;             if (rI < I1) { transpose_item(F.in[I_CWIN], 1024, 8192, (bf16*)(F.ws + WS_W1), scr, rI, F.lane, RowW1()); continue; } rI -= I1;
;             transpose_item(F.in[I_CWOUT], 2048, 1024, (bf16*)(F.ws + WS_W2), scr, rI, F.lane, RowId());
;         }
;     }
.LBB0_31:
.LBB0_32:
	v_readlane_b32 s0, v253, 23
	v_lshlrev_b32_e32 v6, 3, v0
	s_mulk_i32 s0, 0x4100
	v_mov_b32_e32 v3, 0
	v_and_b32_e32 v6, 56, v6
	s_add_i32 s0, s0, 0
	v_lshrrev_b32_e32 v1, 4, v209
	v_lshlrev_b32_e32 v2, 2, v12
	v_lshrrev_b32_e32 v13, 3, v209
	v_mul_u32_u24_e32 v8, 0x104, v6
	v_lshlrev_b32_e32 v6, 1, v6
	v_mov_b32_e32 v7, v3
	v_add_u32_e32 v28, s0, v2
	v_mul_u32_u24_e32 v29, 0x104, v1
	v_lshl_add_u64 v[10:11], s[56:57], 0, v[6:7]
	s_mov_b64 s[4:5], 0x1f400000
	v_lshlrev_b32_e32 v9, 2, v13
	v_lshl_add_u64 v[4:5], s[72:73], 0, v[2:3]
	v_lshl_add_u64 v[6:7], v[10:11], 0, s[4:5]
	v_add3_u32 v14, s0, v8, v9
	v_or_b32_e32 v17, 24, v13
	v_or_b32_e32 v19, 40, v13
	v_or_b32_e32 v21, 56, v13
	v_lshl_add_u64 v[8:9], s[68:69], 0, v[2:3]
	s_mov_b64 s[4:5], 0x1e400000
	v_mov_b32_e32 v2, 0x60
	v_add_u32_e32 v28, v28, v29
	s_lshl_b32 s3, s84, 3
	s_cmp_lg_u32 s84, 0x100
	s_cbranch_scc1 .Lp0tr_keep
	s_movk_i32 s3, 0x200
	s_cmpk_lt_i32 s2, 0x600
	s_cselect_b32 s3, 0x1000, s3
.Lp0tr_keep:
	s_mov_b32 s1, 0
	v_or_b32_e32 v15, 8, v13
	v_or_b32_e32 v16, 16, v13
	v_or_b32_e32 v18, 32, v13
	v_or_b32_e32 v20, 48, v13
	v_lshl_add_u64 v[10:11], v[10:11], 0, s[4:5]
	v_and_or_b32 v22, v17, 15, 32
	v_or_b32_e32 v23, 64, v13
	v_and_or_b32 v24, v19, 15, 64
	v_or_b32_e32 v25, 0x60, v13
	v_and_or_b32 v26, v21, 15, v2
	s_lshl_b32 s8, s2, 6
	s_lshl_b32 s9, s3, 6
	s_lshl_b32 s10, s2, 8
	s_lshl_b32 s11, s3, 8
	s_lshl_b32 s12, s2, 1
	s_lshl_b32 s13, s3, 1
	v_lshlrev_b32_e32 v27, 12, v1
	v_add_u32_e32 v29, 0x410, v28
	v_add_u32_e32 v30, 0x418, v28
	v_add_u32_e32 v31, 0x820, v28
	v_add_u32_e32 v32, 0x828, v28
	v_add_u32_e32 v33, 0xc30, v28
	v_add_u32_e32 v34, 0xc38, v28
	v_add_u32_e32 v35, 0x1040, v28
	v_add_u32_e32 v36, 0x1048, v28
	v_add_u32_e32 v37, 0x1450, v28
	v_add_u32_e32 v38, 0x1458, v28
	v_add_u32_e32 v39, 0x1860, v28
	v_add_u32_e32 v40, 0x1868, v28
	v_add_u32_e32 v41, 0x1c70, v28
	v_add_u32_e32 v42, 0x1c78, v28
	v_add_u32_e32 v43, 0x2080, v28
	v_add_u32_e32 v44, 0x2088, v28
	v_add_u32_e32 v45, 0x2490, v28
	v_add_u32_e32 v46, 0x2498, v28
	v_add_u32_e32 v47, 0x28a0, v28
	v_add_u32_e32 v48, 0x28a8, v28
	v_add_u32_e32 v49, 0x2cb0, v28
	v_add_u32_e32 v50, 0x2cb8, v28
	v_add_u32_e32 v51, 0x30c0, v28
	v_add_u32_e32 v52, 0x30c8, v28
	v_add_u32_e32 v53, 0x34d0, v28
	v_add_u32_e32 v54, 0x34d8, v28
	s_branch .LBB0_34

; __device__ __forceinline__ unsigned xb_ld(unsigned* p)              { return __hip_atomic_load(p, __ATOMIC_RELAXED, __HIP_MEMORY_SCOPE_AGENT); }
; __device__ __forceinline__ void phase_mod0(Frame& F) {
;     { if (F.tid == 0) { unsigned* cnt = (unsigned*)(F.ws + WS_CTL) + CW_MOD; unsigned sp = 0; while (xb_ld(cnt) < 2u * 96u && ++sp < (1u << 22)) __builtin_amdgcn_s_sleep(2);
;           asm volatile("buffer_inv sc0\n s_waitcnt vmcnt(0)" ::: "memory"); }
;       __syncthreads(); }
;     const int gw = F.bid * 8 + F.wave, NGW = F.G * 8; const float* mod = (const float*)(F.ws + WS_MOD);
;     for (int row = gw; row < RT; row += NGW) {
;         const bool isctx = row >= RL; const int rho = isctx ? 2 : row / SEQ;
;         const float* src = isctx ? F.in[I_CTX] + (size_t)(row - RL) * D : F.in[I_X] + (size_t)row * D;
;         f32x4 v[4];
; #pragma unroll
;         for (int j = 0; j < 4; ++j) { const int idx = 256 * j + 4 * F.lane; const f32x4 xv = __builtin_nontemporal_load((const f32x4*)(src + idx));
;             const f32x4 sh = *(const f32x4*)(mod + rho * 3072 + idx), sc = *(const f32x4*)(mod + rho * 3072 + 1024 + idx);
;             v[j] = xv * (1.0f + sc) + sh; }
;         store_row_blk64((char*)F.ws + WS_HX, (size_t)row, F.lane, v);
;         if (!isctx) { const int b = row / SEQ, t = row % SEQ; store_row_blk64((char*)F.out, (size_t)b * SEQ + (size_t)(t % GRIDW) * 256 + t / GRIDW, F.lane, v); }
;     }
.LBB0_86:
	s_or_b64 exec, exec, s[0:1]
	s_lshl_b32 s0, s92, 3
	v_readlane_b32 s1, v253, 23
	s_add_i32 s0, s0, s1
	s_cmp_gt_i32 s0, 0x81ff
	s_barrier
	s_cbranch_scc1 .LBB0_97
	v_lshlrev_b32_e32 v2, 3, v0
	v_mov_b32_e32 v3, 0
	v_lshrrev_b32_e32 v1, 4, v209
	v_and_b32_e32 v2, 0x78, v2
	v_lshlrev_b32_e32 v8, 2, v209
	v_lshl_add_u64 v[6:7], s[56:57], 0, v[2:3]
	v_mul_u32_u24_e32 v4, 0x410000, v1
	v_mov_b32_e32 v5, v3
	v_or_b32_e32 v10, 0x100, v8
	v_or_b32_e32 v12, 0x200, v8
	v_or_b32_e32 v14, 0x300, v8
	v_lshl_add_u64 v[6:7], v[6:7], 0, v[4:5]
	s_mov_b64 s[8:9], 0x6200000
	s_lshl_b32 s2, s84, 3
	v_lshl_add_u64 v[6:7], v[6:7], 0, s[8:9]
	s_mov_b32 s1, 0
	v_lshlrev_b32_e32 v1, 2, v8
	v_lshlrev_b32_e32 v16, 2, v10
	v_lshlrev_b32_e32 v17, 2, v12
	v_lshlrev_b32_e32 v18, 2, v14
	s_mov_b32 s3, 0x1040000
	s_mov_b32 s18, 0x2080000
	s_mov_b32 s100, -1
	s_ashr_i32 s11, s0, 31
	s_mov_b32 s10, s0
	s_lshl_b64 s[12:13], s[10:11], 12
	s_add_u32 s12, s36, s12
	s_addc_u32 s13, s37, s13
	global_load_dwordx4 v[100:103], v1, s[12:13] nt
	global_load_dwordx4 v[104:107], v1, s[12:13] offset:1024 nt
	global_load_dwordx4 v[108:111], v1, s[12:13] offset:2048 nt
	global_load_dwordx4 v[112:115], v1, s[12:13] offset:3072 nt
.Lp1_loop:
	s_ashr_i32 s10, s0, 14
	s_cmp_eq_u32 s10, s100
	s_cbranch_scc1 .Lp1_modok
	s_mov_b32 s100, s10
	s_mul_i32 s14, s10, 0xc00
	s_mov_b32 s15, 0
	s_lshl_b64 s[14:15], s[14:15], 2
	v_readlane_b32 s16, v253, 24
	v_readlane_b32 s17, v253, 25
	s_nop 3
	s_add_u32 s14, s16, s14
	s_addc_u32 s15, s17, s15
	s_add_u32 s16, s14, 0x1000
	s_addc_u32 s17, s15, 0
	global_load_dwordx4 v[68:71], v1, s[16:17]
	global_load_dwordx4 v[72:75], v16, s[16:17]
	global_load_dwordx4 v[76:79], v17, s[16:17]
	global_load_dwordx4 v[80:83], v18, s[16:17]
	global_load_dwordx4 v[84:87], v1, s[14:15]
	global_load_dwordx4 v[88:91], v1, s[14:15] offset:1024
	global_load_dwordx4 v[92:95], v1, s[14:15] offset:2048
	global_load_dwordx4 v[96:99], v1, s[14:15] offset:3072
	s_waitcnt vmcnt(0)
	v_pk_add_f32 v[68:69], v[68:69], 1.0 op_sel_hi:[1,0]
	v_pk_add_f32 v[70:71], v[70:71], 1.0 op_sel_hi:[1,0]
	v_pk_add_f32 v[72:73], v[72:73], 1.0 op_sel_hi:[1,0]
	v_pk_add_f32 v[74:75], v[74:75], 1.0 op_sel_hi:[1,0]
	v_pk_add_f32 v[76:77], v[76:77], 1.0 op_sel_hi:[1,0]
	v_pk_add_f32 v[78:79], v[78:79], 1.0 op_sel_hi:[1,0]
	v_pk_add_f32 v[80:81], v[80:81], 1.0 op_sel_hi:[1,0]
	v_pk_add_f32 v[82:83], v[82:83], 1.0 op_sel_hi:[1,0]
.Lp1_modok:
	s_waitcnt vmcnt(8)
	v_mov_b32_e32 v28, v100
	v_mov_b32_e32 v29, v101
	v_mov_b32_e32 v30, v102
	v_mov_b32_e32 v31, v103
	v_mov_b32_e32 v40, v104
	v_mov_b32_e32 v41, v105
	v_mov_b32_e32 v42, v106
	v_mov_b32_e32 v43, v107
	v_mov_b32_e32 v44, v108
	v_mov_b32_e32 v45, v109
	v_mov_b32_e32 v46, v110
	v_mov_b32_e32 v47, v111
	v_mov_b32_e32 v52, v112
	v_mov_b32_e32 v53, v113
	v_mov_b32_e32 v54, v114
	v_mov_b32_e32 v55, v115
	s_ashr_i32 s11, s0, 31
	s_mov_b32 s10, s0
	s_lshl_b64 s[10:11], s[10:11], 7
	v_lshl_add_u64 v[60:61], v[6:7], 0, s[10:11]
	v_add_co_u32_e32 v62, vcc, s3, v60
	s_nop 1
	v_addc_co_u32_e32 v63, vcc, 0, v61, vcc
	v_add_co_u32_e32 v64, vcc, s18, v60
	s_nop 1
	v_addc_co_u32_e32 v65, vcc, 0, v61, vcc
	v_add_co_u32_e32 v66, vcc, 0x30c0000, v60
	s_nop 1
	v_addc_co_u32_e32 v67, vcc, 0, v61, vcc
	s_add_i32 s101, s0, s2
	s_cmp_lt_i32 s101, 0x8000
	s_cbranch_scc0 .Lp1_nopf
	s_ashr_i32 s11, s101, 31
	s_mov_b32 s10, s101
	s_lshl_b64 s[12:13], s[10:11], 12
	s_add_u32 s12, s36, s12
	s_addc_u32 s13, s37, s13
	global_load_dwordx4 v[100:103], v1, s[12:13] nt
	global_load_dwordx4 v[104:107], v1, s[12:13] offset:1024 nt
	global_load_dwordx4 v[108:111], v1, s[12:13] offset:2048 nt
	global_load_dwordx4 v[112:115], v1, s[12:13] offset:3072 nt
.Lp1_nopf:
	v_pk_fma_f32 v[10:11], v[30:31], v[70:71], v[86:87]
	v_pk_fma_f32 v[8:9], v[28:29], v[68:69], v[84:85]
	v_pk_fma_f32 v[28:29], v[42:43], v[74:75], v[90:91]
	v_pk_fma_f32 v[12:13], v[40:41], v[72:73], v[88:89]
	v_pk_fma_f32 v[22:23], v[46:47], v[78:79], v[94:95]
	v_pk_fma_f32 v[20:21], v[44:45], v[76:77], v[92:93]
	v_pk_fma_f32 v[26:27], v[54:55], v[82:83], v[98:99]
	v_pk_fma_f32 v[24:25], v[52:53], v[80:81], v[96:97]
	v_cvt_pk_bf16_f32 v14, v8, v9
	v_cvt_pk_bf16_f32 v15, v10, v11
	v_cvt_pk_bf16_f32 v12, v12, v13
	v_cvt_pk_bf16_f32 v13, v28, v29
	v_cvt_pk_bf16_f32 v10, v20, v21
	v_cvt_pk_bf16_f32 v11, v22, v23
	v_cvt_pk_bf16_f32 v8, v24, v25
	v_cvt_pk_bf16_f32 v9, v26, v27
	global_store_dwordx2 v[60:61], v[14:15], off
	global_store_dwordx2 v[62:63], v[12:13], off
	global_store_dwordx2 v[64:65], v[10:11], off
	global_store_dwordx2 v[66:67], v[8:9], off
	s_ashr_i32 s8, s0, 31
	s_lshr_b32 s8, s8, 18
	s_add_i32 s9, s0, s8
	s_ashr_i32 s8, s9, 14
	s_and_b32 s9, s9, 0xc000
	s_sub_i32 s11, s0, s9
	s_sext_i32_i16 s10, s11
	s_bfe_u32 s10, s10, 0x60019
	s_add_i32 s12, s11, s10
	s_sext_i32_i16 s10, s12
	s_and_b32 s12, s12, 0xffc0
	v_readlane_b32 s36, v253, 7
	s_lshr_b32 s10, s10, 6
	s_sub_i32 s12, s11, s12
	v_readlane_b32 s44, v253, 15
	v_readlane_b32 s45, v253, 16
	s_ashr_i32 s9, s8, 31
	s_bfe_i64 s[12:13], s[12:13], 0x100000
	s_bfe_i64 s[10:11], s[10:11], 0x100000
	v_readlane_b32 s46, v253, 17
	v_readlane_b32 s47, v253, 18
	v_readlane_b32 s48, v253, 19
	v_readlane_b32 s49, v253, 20
	v_readlane_b32 s50, v253, 21
	v_readlane_b32 s51, v253, 22
	s_mov_b64 s[20:21], s[44:45]
	s_lshl_b64 s[12:13], s[12:13], 15
	s_lshl_b64 s[8:9], s[8:9], 21
	s_lshl_b64 s[10:11], s[10:11], 7
	s_mov_b64 s[26:27], s[50:51]
	s_add_u32 s12, s26, s12
	s_addc_u32 s13, s27, s13
	s_add_u32 s8, s12, s8
	s_addc_u32 s9, s13, s9
	s_add_u32 s8, s8, s10
	s_addc_u32 s9, s9, s11
	v_lshl_add_u64 v[20:21], s[8:9], 0, v[2:3]
	v_lshl_add_u64 v[20:21], v[20:21], 0, v[4:5]
	global_store_dwordx2 v[20:21], v[14:15], off
	v_add_co_u32_e32 v14, vcc, 0x1040000, v20
	v_readlane_b32 s37, v253, 8
	s_nop 0
	v_addc_co_u32_e32 v15, vcc, 0, v21, vcc
	global_store_dwordx2 v[14:15], v[12:13], off
	v_add_co_u32_e32 v12, vcc, 0x2080000, v20
	v_readlane_b32 s38, v253, 9
	v_readlane_b32 s39, v253, 10
	v_readlane_b32 s40, v253, 11
	v_readlane_b32 s41, v253, 12
	v_readlane_b32 s42, v253, 13
	v_readlane_b32 s43, v253, 14
	v_addc_co_u32_e32 v13, vcc, 0, v21, vcc
	s_mov_b64 s[22:23], s[46:47]
	s_mov_b64 s[24:25], s[48:49]
	v_readlane_b32 s36, v253, 26
	v_readlane_b32 s26, v253, 42
	global_store_dwordx2 v[12:13], v[10:11], off
	v_add_co_u32_e32 v10, vcc, 0x30c0000, v20
	v_readlane_b32 s37, v253, 27
	v_readlane_b32 s40, v253, 30
	v_readlane_b32 s41, v253, 31
	v_readlane_b32 s48, v253, 38
	v_readlane_b32 s49, v253, 39
	v_readlane_b32 s50, v253, 40
	v_readlane_b32 s51, v253, 41
	v_readlane_b32 s27, v253, 43
	v_addc_co_u32_e32 v11, vcc, 0, v21, vcc
	v_readlane_b32 s38, v253, 28
	v_readlane_b32 s39, v253, 29
	v_readlane_b32 s42, v253, 32
	v_readlane_b32 s43, v253, 33
	v_readlane_b32 s44, v253, 34
	v_readlane_b32 s45, v253, 35
	v_readlane_b32 s46, v253, 36
	v_readlane_b32 s47, v253, 37
	global_store_dwordx2 v[10:11], v[8:9], off
	s_add_i32 s0, s0, s2
	s_cmp_lt_i32 s0, 0x8000
	s_cbranch_scc1 .Lp1_loop
	s_cmp_lt_i32 s0, 0x8200
	s_cbranch_scc0 .LBB0_97
	s_branch .LBB0_89
